# strategy: idle last-round workgroups of the in-proj and gate/up GEMMs convert part of the out-proj / down-proj weights (400 + 112 tiles moved out of the HBM-bound P0/P1)
# speedup vs baseline: 1.0046x; 1.0046x over previous
; #define LAS __attribute__((address_space(3)))
; __global__ void __launch_bounds__(512, 2) fwd_mega(Params prm) {
;     extern __shared__ __attribute__((aligned(16))) unsigned char lds_raw[];
;     cg::grid_group grid = cg::this_grid();
;     Frame F;
;     F.lds = (LAS unsigned char*)lds_raw; F.tid = threadIdx.x; F.lane = F.tid & 63; F.wave = __builtin_amdgcn_readfirstlane(F.tid >> 6); F.G = gridDim.x; F.bid = blockIdx.x;
; #pragma unroll
;     for (int i = 0; i < 23; ++i) F.in[i] = prm.in[i];
;     F.out = prm.out; F.ws = prm.ws;
;     unsigned char* ws = F.ws;
;     const int lo = prm.ph_lo, hi = prm.ph_hi;
;     ...
;     const float* mod = (const float*)(ws + WS_MOD);
;     volatile LAS unsigned* xst = (volatile LAS unsigned*)(F.lds + LDS_BYTES - 16);
;     if (F.tid == 0) { xst[0] = 0u; xst[1] = 0u; }
;     __syncthreads();
_Z8fwd_mega6Params:
	s_mov_b64 s[98:99], s[0:1]
	s_mov_b32 s33, s2
	s_load_dword s2, s[0:1], 0xe0
	s_load_dwordx2 s[88:89], s[0:1], 0xd8
	s_load_dwordx4 s[84:87], s[0:1], 0xc0
	s_add_u32 s10, s0, 0xd8
	v_and_b32_e32 v144, 0x3ff, v0
	s_addc_u32 s11, s1, 0
	v_readfirstlane_b32 s8, v144
	s_mov_b32 s81, 0
	s_waitcnt lgkmcnt(0)
	v_writelane_b32 v245, s2, 0
	v_cmp_eq_u32_e64 s[4:5], 0, v144
	s_mov_b64 s[2:3], exec
	s_nop 0
	v_writelane_b32 v245, s4, 1
	s_nop 1
	v_writelane_b32 v245, s5, 2
	s_and_b64 s[4:5], s[2:3], s[4:5]
	s_mov_b64 exec, s[4:5]
	s_cbranch_execz .LBB0_2
	s_add_i32 s4, 0, 0x23ff0
	v_mov_b32_e32 v1, 0
	v_mov_b32_e32 v2, s4
	s_add_i32 s4, 0, 0x23ff4
	ds_write_b32 v2, v1
	v_mov_b32_e32 v2, s4
	ds_write_b32 v2, v1

; #define LAS __attribute__((address_space(3)))
; __device__ __forceinline__ TileDesc tile_desc(const Frame& F, int t) {
;     unsigned char* ws = F.ws; TileDesc d; int NT, idx; d.kind = 0;
;     if (t < 1536) { d.src = F.in[12]; d.ldn = NMOD; d.K = D; NT = 48; idx = t; d.dst = (bf16_t*)(ws + WS_WADA); }
;     else if (t < 2240) { d.src = F.in[14]; d.ldn = INW; d.K = D; NT = 22; idx = t - 1536; d.dst = (bf16_t*)(ws + WS_WIN); }
;     else if (t < 2496) { d.src = F.in[19]; d.ldn = D; d.K = D; NT = 8; idx = t - 2240; d.dst = (bf16_t*)(ws + WS_WOUT); }
;     else if (t < 3200) { d.src = F.in[20]; d.ldn = DFF; d.K = D; NT = 22; idx = t - 2496; d.dst = (bf16_t*)(ws + WS_WGU); d.kind = 1; }
;     else if (t < 3904) { d.src = F.in[21]; d.ldn = DFF; d.K = D; NT = 22; idx = t - 3200; d.dst = (bf16_t*)(ws + WS_WGU); d.kind = 2; }
;     else { d.src = F.in[22]; d.ldn = D; d.K = DFF; NT = 8; idx = t - 3904; d.dst = (bf16_t*)(ws + WS_WDN); }
;     d.n0 = (idx % NT) * 256; d.k0 = (idx / NT) * 64; return d;
; __global__ void __launch_bounds__(512, 2) fwd_mega(Params prm) {
;     ...
;     F.lds = (LAS unsigned char*)lds_raw; F.tid = threadIdx.x; F.lane = F.tid & 63; F.wave = __builtin_amdgcn_readfirstlane(F.tid >> 6); F.G = gridDim.x; F.bid = blockIdx.x;
; #pragma unroll
;     for (int i = 0; i < 23; ++i) F.in[i] = prm.in[i];
;     F.out = prm.out; F.ws = prm.ws;
;     unsigned char* ws = F.ws;
;     const int lo = prm.ph_lo, hi = prm.ph_hi;
.LBB0_7:
	s_waitcnt lgkmcnt(0)
	v_writelane_b32 v245, s12, 21
	s_lshr_b32 s80, s8, 6
	s_cmp_lt_i32 s86, 1
	v_writelane_b32 v245, s13, 22
	v_writelane_b32 v245, s14, 23
	v_writelane_b32 v245, s15, 24
	v_writelane_b32 v245, s16, 25
	v_writelane_b32 v245, s17, 26
	v_writelane_b32 v245, s18, 27
	v_writelane_b32 v245, s19, 28
	v_writelane_b32 v245, s20, 29
	v_writelane_b32 v245, s21, 30
	v_writelane_b32 v245, s22, 31
	v_writelane_b32 v245, s23, 32
	v_writelane_b32 v245, s24, 33
	v_writelane_b32 v245, s25, 34
	v_writelane_b32 v245, s26, 35
	v_writelane_b32 v245, s27, 36
	s_load_dwordx16 s[12:27], s[0:1], 0x0
	s_cselect_b64 s[2:3], -1, 0
	s_cmp_gt_i32 s87, 0
	s_cselect_b64 s[4:5], -1, 0
	v_and_b32_e32 v160, 63, v144
	s_waitcnt lgkmcnt(0)
	v_writelane_b32 v245, s12, 37
	s_nop 1
	v_writelane_b32 v245, s13, 38
	v_writelane_b32 v245, s14, 39
	v_writelane_b32 v245, s15, 40
	v_writelane_b32 v245, s16, 41
	v_writelane_b32 v245, s17, 42
	v_writelane_b32 v245, s18, 43
	v_writelane_b32 v245, s19, 44
	v_writelane_b32 v245, s20, 45
	v_writelane_b32 v245, s21, 46
	v_writelane_b32 v245, s22, 47
	v_writelane_b32 v245, s23, 48
	v_writelane_b32 v245, s24, 49
	v_writelane_b32 v245, s25, 50
	v_writelane_b32 v245, s26, 51
	v_writelane_b32 v245, s27, 52
	s_and_b64 s[12:13], s[2:3], s[4:5]
	s_andn2_b64 vcc, exec, s[12:13]
	v_writelane_b32 v245, s8, 53
	s_cbranch_vccnz .LBB0_71
	s_cmpk_gt_i32 s33, 0x94f
	s_cbranch_scc1 .LBB0_27
	s_cmpk_lt_i32 s33, 0x600
	s_mov_b32 s4, 48
	s_cbranch_scc1 .LBB0_13
	s_cmpk_gt_u32 s33, 0x8bf
	s_cbranch_scc0 .LBB0_14
	s_load_dwordx16 s[16:31], s[0:1], 0x80
	s_add_i32 s15, s33, 0xfffff740
	s_add_u32 s2, s84, 0x4600000
	s_addc_u32 s3, s85, 0
	s_waitcnt lgkmcnt(0)
	s_mov_b64 s[8:9], s[22:23]
	s_cbranch_execz .LBB0_15
	s_mov_b64 s[6:7], 0x800
	s_mov_b32 s4, 8
	s_branch .LBB0_16

; #define LAS __attribute__((address_space(3)))
; __device__ __forceinline__ void convert_tiles(const Frame& F, int tlo, int thi, int wb, int nw) {
;     ...
;     for (;;) {
; #pragma unroll
;         for (int i = 0; i < 8; ++i) { LAS float* tp = tile + (i * 8 + F.wave) * 257 + F.lane * 4; tp[0] = v[i][0]; tp[1] = v[i][1]; tp[2] = v[i][2]; tp[3] = v[i][3]; }
;         __syncthreads();
;         const int tn = t + nw; const bool more = tn < thi; TileDesc dn = d;
;         if (more) { dn = tile_desc(F, tn);
; #pragma unroll
;             for (int i = 0; i < 8; ++i) v[i] = __builtin_nontemporal_load((const f32x4*)(dn.src + (size_t)(dn.k0 + i * 8 + F.wave) * dn.ldn + dn.n0 + F.lane * 4)); }
; #pragma unroll
;         for (int it = 0; it < 4; ++it) { const int item = it * 512 + F.tid, n = item >> 3, kg = item & 7;
;             float f[8];
; #pragma unroll
;             for (int j = 0; j < 8; ++j) f[j] = tile[(kg * 8 + j) * 257 + n];
;             const int nn = d.n0 + n; const int row = d.kind == 0 ? nn : (((nn >> 7) << 8) + (nn & 127) + (d.kind == 2 ? 128 : 0));
;             *(u32x4*)(d.dst + (size_t)row * d.K + d.k0 + kg * 8) = pack8(f); }
;         __syncthreads();
;         if (!more) break;
;         t = tn; d = dn;
.LBB0_20:
	s_add_i32 s5, s5, s88
	s_cmpk_gt_i32 s5, 0x94f
	s_cselect_b64 s[18:19], -1, 0
	v_add_u32_e32 v37, 0xe0e8, v41
	s_and_b64 vcc, exec, s[18:19]
	s_mov_b32 s23, s14
	s_mov_b32 s20, s4
	s_waitcnt vmcnt(7)
	ds_write2_b32 v41, v2, v3 offset1:1
	ds_write2_b32 v41, v4, v5 offset0:2 offset1:3
	s_waitcnt vmcnt(6)
	ds_write2_b32 v42, v6, v7 offset1:1
	ds_write2_b32 v43, v8, v9 offset1:1
	s_waitcnt vmcnt(5)
	ds_write2_b32 v44, v10, v11 offset1:1
	ds_write2_b32 v45, v12, v13 offset1:1
	s_waitcnt vmcnt(4)
	ds_write2_b32 v46, v14, v15 offset1:1
	ds_write2_b32 v47, v16, v17 offset1:1
	s_waitcnt vmcnt(3)
	ds_write2_b32 v48, v18, v19 offset1:1
	ds_write2_b32 v49, v20, v21 offset1:1
	s_waitcnt vmcnt(2)
	ds_write2_b32 v53, v22, v23 offset1:1
	ds_write2_b32 v54, v24, v25 offset1:1
	s_waitcnt vmcnt(1)
	ds_write2_b32 v55, v26, v27 offset1:1
	ds_write2_b32 v56, v28, v29 offset1:1
	s_waitcnt vmcnt(0)
	ds_write2_b32 v57, v30, v31 offset1:1
	ds_write2_b32 v37, v32, v33 offset1:1
	s_waitcnt lgkmcnt(0)
	s_barrier
	s_cbranch_vccnz .LBB0_19
	s_cmpk_lt_i32 s5, 0x600
	s_cbranch_scc1 .LBB0_17
	s_cmpk_gt_u32 s5, 0x8bf
	s_cbranch_scc0 .LBB0_25
	s_load_dwordx16 s[36:51], s[0:1], 0x80
	s_add_i32 s15, s5, 0xfffff740
	s_waitcnt lgkmcnt(0)
	s_mov_b64 s[24:25], s[42:43]
	s_cbranch_execz .LBB0_26
	s_mov_b64 s[22:23], 0x800
	s_mov_b32 s20, 8
	s_mov_b64 s[16:17], s[6:7]
	s_branch .LBB0_18

; __device__ __forceinline__ TileDesc tile_desc(const Frame& F, int t) {
;     unsigned char* ws = F.ws; TileDesc d; int NT, idx; d.kind = 0;
;     if (t < 1536) { d.src = F.in[12]; d.ldn = NMOD; d.K = D; NT = 48; idx = t; d.dst = (bf16_t*)(ws + WS_WADA); }
;     else if (t < 2240) { d.src = F.in[14]; d.ldn = INW; d.K = D; NT = 22; idx = t - 1536; d.dst = (bf16_t*)(ws + WS_WIN); }
;     else if (t < 2496) { d.src = F.in[19]; d.ldn = D; d.K = D; NT = 8; idx = t - 2240; d.dst = (bf16_t*)(ws + WS_WOUT); }
;     else if (t < 3200) { d.src = F.in[20]; d.ldn = DFF; d.K = D; NT = 22; idx = t - 2496; d.dst = (bf16_t*)(ws + WS_WGU); d.kind = 1; }
;     else if (t < 3904) { d.src = F.in[21]; d.ldn = DFF; d.K = D; NT = 22; idx = t - 3200; d.dst = (bf16_t*)(ws + WS_WGU); d.kind = 2; }
;     else { d.src = F.in[22]; d.ldn = D; d.K = DFF; NT = 8; idx = t - 3904; d.dst = (bf16_t*)(ws + WS_WDN); }
;     d.n0 = (idx % NT) * 256; d.k0 = (idx / NT) * 64; return d;
; __global__ void __launch_bounds__(512, 2) fwd_mega(Params prm) {
;     ...
;     if (IN(1)) { { const int cb = F.G > 96 ? 48 : 0;
;           if (F.bid >= cb) convert_tiles(F, 2496, 4608, F.bid - cb, F.G - cb); }
.LBB0_83:
	s_cmp_lt_i32 s86, 2
	s_cselect_b64 s[4:5], -1, 0
	s_add_u32 s6, s84, 0x9100000
	s_addc_u32 s7, s85, 0
	s_and_b64 s[14:15], s[4:5], s[2:3]
	v_writelane_b32 v245, s6, 54
	s_andn2_b64 vcc, exec, s[14:15]
	s_nop 0
	v_writelane_b32 v245, s7, 55
	s_cbranch_vccnz .LBB0_143
	s_cmpk_gt_i32 s88, 0x60
	s_waitcnt lgkmcnt(0)
	s_cselect_b32 s16, 48, 0
	s_cmp_lt_i32 s33, s16
	s_cbranch_scc1 .LBB0_115
	s_sub_i32 s8, s33, s16
	s_cmpk_gt_u32 s8, 0x6af
	s_cbranch_scc1 .LBB0_115
	s_cmpk_lt_u32 s8, 0x2c0
	s_mov_b32 s13, 1
	s_cbranch_scc1 .LBB0_90
	s_cmpk_gt_u32 s8, 0x57f
	s_cbranch_scc0 .LBB0_91
	s_load_dwordx16 s[36:51], s[0:1], 0x80
	s_add_i32 s9, s8, 0xfffffa80
	s_waitcnt lgkmcnt(0)
	s_mov_b64 s[4:5], s[48:49]
	s_cbranch_execz .LBB0_92
	s_mov_b64 s[6:7], 0x7a00000
	s_mov_b64 s[2:3], 0x800
	s_movk_i32 s24, 0x1600
	s_mov_b32 s13, 0
	s_mov_b32 s12, 8
	s_branch .LBB0_93

; #define LAS __attribute__((address_space(3)))
; __device__ __forceinline__ void convert_tiles(const Frame& F, int tlo, int thi, int wb, int nw) {
;     ...
;     for (;;) {
; #pragma unroll
;         for (int i = 0; i < 8; ++i) { LAS float* tp = tile + (i * 8 + F.wave) * 257 + F.lane * 4; tp[0] = v[i][0]; tp[1] = v[i][1]; tp[2] = v[i][2]; tp[3] = v[i][3]; }
;         __syncthreads();
;         const int tn = t + nw; const bool more = tn < thi; TileDesc dn = d;
;         if (more) { dn = tile_desc(F, tn);
; #pragma unroll
;             for (int i = 0; i < 8; ++i) v[i] = __builtin_nontemporal_load((const f32x4*)(dn.src + (size_t)(dn.k0 + i * 8 + F.wave) * dn.ldn + dn.n0 + F.lane * 4)); }
; #pragma unroll
;         for (int it = 0; it < 4; ++it) { const int item = it * 512 + F.tid, n = item >> 3, kg = item & 7;
;             float f[8];
; #pragma unroll
;             for (int j = 0; j < 8; ++j) f[j] = tile[(kg * 8 + j) * 257 + n];
;             const int nn = d.n0 + n; const int row = d.kind == 0 ? nn : (((nn >> 7) << 8) + (nn & 127) + (d.kind == 2 ? 128 : 0));
;             *(u32x4*)(d.dst + (size_t)row * d.K + d.k0 + kg * 8) = pack8(f); }
;         __syncthreads();
;         if (!more) break;
;         t = tn; d = dn;
;     }
.LBB0_96:
	s_cmp_eq_u32 s13, 0
	v_add_u32_e32 v35, s27, v36
	ds_read_b32 v52, v45 offset:1028
	ds_read_b32 v53, v45 offset:3084
	ds_read_b32 v54, v45 offset:5140
	ds_read_b32 v55, v45 offset:7196
	ds_read_b32 v56, v45 offset:6168
	ds_read_b32 v57, v45 offset:4112
	ds_read_b32 v58, v45 offset:2056
	ds_read_b32 v59, v45
	s_cselect_b64 vcc, -1, 0
	s_cmp_eq_u32 s13, 2
	v_lshlrev_b32_e32 v60, 1, v35
	s_cselect_b32 s19, 0x80, 0
	s_ashr_i32 s13, s12, 31
	v_and_b32_e32 v60, 0xffffff00, v60
	s_lshl_b64 s[12:13], s[12:13], 1
	v_or3_b32 v60, v36, v60, s19
	s_add_u32 s10, s10, s12
	v_cndmask_b32_e32 v35, v60, v35, vcc
	s_addc_u32 s11, s11, s13
	s_waitcnt lgkmcnt(0)
	v_cvt_pk_bf16_f32 v52, v59, v52
	v_cvt_pk_bf16_f32 v53, v58, v53
	v_cvt_pk_bf16_f32 v54, v57, v54
	v_cvt_pk_bf16_f32 v55, v56, v55
	v_mad_u64_u32 v[56:57], s[12:13], v35, s24, 0
	v_ashrrev_i32_e32 v59, 31, v35
	v_mov_b32_e32 v58, v57
	v_mad_u64_u32 v[58:59], s[12:13], v59, s24, v[58:59]
	v_mov_b32_e32 v57, v58
	v_lshl_add_u64 v[56:57], v[56:57], 1, s[10:11]
	v_mov_b32_e32 v35, v33
	v_lshl_add_u64 v[56:57], v[56:57], 0, v[34:35]
	global_store_dwordx4 v[56:57], v[52:55], off
	ds_read_b32 v53, v46 offset:1028
	ds_read_b32 v54, v46 offset:3084
	ds_read_b32 v55, v46 offset:5140
	ds_read_b32 v56, v46 offset:7196
	ds_read_b32 v57, v46 offset:6168
	ds_read_b32 v58, v46 offset:4112
	ds_read_b32 v59, v46 offset:2056
	ds_read_b32 v60, v46
	v_add_u32_e32 v52, s27, v37
	v_lshlrev_b32_e32 v61, 1, v52
	v_and_b32_e32 v61, 0xffffff00, v61
	v_or3_b32 v61, v38, v61, s19
	v_cndmask_b32_e32 v61, v61, v52, vcc
	s_waitcnt lgkmcnt(0)
	v_cvt_pk_bf16_f32 v52, v60, v53
	v_cvt_pk_bf16_f32 v53, v59, v54
	v_cvt_pk_bf16_f32 v54, v58, v55
	v_cvt_pk_bf16_f32 v55, v57, v56
	v_mad_u64_u32 v[56:57], s[12:13], v61, s24, 0
	v_ashrrev_i32_e32 v59, 31, v61
	v_mov_b32_e32 v58, v57
	v_mad_u64_u32 v[58:59], s[12:13], v59, s24, v[58:59]
	v_mov_b32_e32 v57, v58
	v_lshl_add_u64 v[56:57], v[56:57], 1, s[10:11]
	v_lshl_add_u64 v[56:57], v[56:57], 0, v[34:35]
	global_store_dwordx4 v[56:57], v[52:55], off
	ds_read_b32 v53, v45 offset:1540
	ds_read_b32 v54, v45 offset:3596
	ds_read_b32 v55, v45 offset:5652
	ds_read_b32 v56, v45 offset:7708
	ds_read_b32 v57, v45 offset:6680
	ds_read_b32 v58, v45 offset:4624
	ds_read_b32 v59, v45 offset:2568
	ds_read_b32 v60, v45 offset:512
	v_add_u32_e32 v52, s27, v39
	v_lshlrev_b32_e32 v61, 1, v52
	v_and_b32_e32 v61, 0xffffff00, v61
	v_or3_b32 v61, v36, v61, s19
	v_cndmask_b32_e32 v61, v61, v52, vcc
	s_waitcnt lgkmcnt(0)
	v_cvt_pk_bf16_f32 v52, v60, v53
	v_cvt_pk_bf16_f32 v53, v59, v54
	v_cvt_pk_bf16_f32 v54, v58, v55
	v_cvt_pk_bf16_f32 v55, v57, v56
	v_mad_u64_u32 v[56:57], s[12:13], v61, s24, 0
	v_ashrrev_i32_e32 v59, 31, v61
	v_mov_b32_e32 v58, v57
	v_mad_u64_u32 v[58:59], s[12:13], v59, s24, v[58:59]
	v_mov_b32_e32 v57, v58
	v_lshl_add_u64 v[56:57], v[56:57], 1, s[10:11]
	v_lshl_add_u64 v[56:57], v[56:57], 0, v[34:35]
	global_store_dwordx4 v[56:57], v[52:55], off
	ds_read_b32 v53, v47 offset:1028
	ds_read_b32 v54, v47 offset:3084
	ds_read_b32 v55, v47 offset:5140
	ds_read_b32 v56, v47 offset:7196
	ds_read_b32 v57, v47 offset:6168
	ds_read_b32 v58, v47 offset:4112
	ds_read_b32 v59, v47 offset:2056
	ds_read_b32 v60, v47
	v_add_u32_e32 v52, s27, v40
	v_lshlrev_b32_e32 v61, 1, v52
	v_and_b32_e32 v61, 0xffffff00, v61
	v_or3_b32 v61, v41, v61, s19
	v_cndmask_b32_e32 v61, v61, v52, vcc
	s_waitcnt lgkmcnt(0)
	v_cvt_pk_bf16_f32 v52, v60, v53
	v_cvt_pk_bf16_f32 v53, v59, v54
	v_cvt_pk_bf16_f32 v54, v58, v55
	v_cvt_pk_bf16_f32 v55, v57, v56
	v_mad_u64_u32 v[56:57], s[12:13], v61, s24, 0
	v_ashrrev_i32_e32 v59, 31, v61
	v_mov_b32_e32 v58, v57
	v_mad_u64_u32 v[58:59], s[12:13], v59, s24, v[58:59]
	v_mov_b32_e32 v57, v58
	s_add_i32 s30, s30, s25
	v_lshl_add_u64 v[56:57], v[56:57], 1, s[10:11]
	s_add_i32 s10, s29, s30
	v_lshl_add_u64 v[56:57], v[56:57], 0, v[34:35]
	s_cmpk_lt_i32 s10, 0x1070
	s_mov_b64 s[10:11], s[16:17]
	s_mov_b32 s24, s31
	s_mov_b32 s12, s35
	s_mov_b32 s27, s18
	s_mov_b32 s13, s34
	global_store_dwordx4 v[56:57], v[52:55], off
	s_barrier
	s_cbranch_scc0 .LBB0_115
.LBB0_97:
	v_add_u32_e32 v35, 0x8080, v42
	s_waitcnt vmcnt(7)
	ds_write2_b32 v42, v0, v1 offset1:1
	ds_write2_b32 v42, v2, v3 offset0:2 offset1:3
	s_waitcnt vmcnt(6)
	ds_write2_b32 v43, v4, v5 offset1:1
	ds_write2_b32 v44, v6, v7 offset1:1
	s_waitcnt vmcnt(5)
	ds_write2_b32 v48, v8, v9 offset1:1
	ds_write2_b32 v49, v10, v11 offset1:1
	s_waitcnt vmcnt(4)
	ds_write2_b32 v50, v12, v13 offset1:1
	ds_write2_b32 v51, v14, v15 offset1:1
	s_waitcnt vmcnt(3)
	ds_write2_b32 v35, v16, v17 offset1:1
	v_add_u32_e32 v35, 0x8088, v42
	ds_write2_b32 v35, v18, v19 offset1:1
	v_add_u32_e32 v35, 0xa0a0, v42
	s_waitcnt vmcnt(2)
	ds_write2_b32 v35, v20, v21 offset1:1
	v_add_u32_e32 v35, 0xa0a8, v42
	ds_write2_b32 v35, v22, v23 offset1:1
	v_add_u32_e32 v35, 0xc0c0, v42
	s_waitcnt vmcnt(1)
	ds_write2_b32 v35, v24, v25 offset1:1
	v_add_u32_e32 v35, 0xc0c8, v42
	s_add_i32 s19, s28, s30
	ds_write2_b32 v35, v26, v27 offset1:1
	v_add_u32_e32 v35, 0xe0e0, v42
	s_add_i32 s26, s26, s25
	s_add_i32 s20, s19, 0x9c0
	s_waitcnt vmcnt(0)
	ds_write2_b32 v35, v28, v29 offset1:1
	v_add_u32_e32 v35, 0xe0e8, v42
	s_cmpk_gt_i32 s20, 0x106f
	s_mov_b32 s35, s12
	s_mov_b32 s18, s27
	ds_write2_b32 v35, v30, v31 offset1:1
	s_waitcnt lgkmcnt(0)
	s_barrier
	s_cbranch_scc1 .LBB0_96
	s_cmpk_lt_i32 s20, 0x600
	s_cbranch_scc1 .LBB0_94
	s_cmpk_gt_u32 s20, 0x8bf
	s_cbranch_scc0 .LBB0_105
	s_cmpk_gt_u32 s20, 0x9bf
	s_cbranch_scc0 .LBB0_106
	s_cmpk_gt_u32 s20, 0xc7f
	s_cbranch_scc0 .LBB0_107
	s_cmpk_gt_u32 s20, 0xf3f
	s_cbranch_scc0 .LBB0_113
	s_load_dwordx16 s[36:51], s[0:1], 0x80
	s_add_i32 s52, s19, 0xfffffa80
	s_waitcnt lgkmcnt(0)
	s_mov_b64 s[22:23], s[48:49]
	s_cbranch_execz .LBB0_114
	s_mov_b64 s[20:21], 0x800
	s_movk_i32 s31, 0x1600
	s_mov_b32 s34, 0
	s_mov_b32 s35, 8
	s_mov_b64 s[16:17], s[2:3]
	s_cbranch_execz .LBB0_108
	s_branch .LBB0_109

; #define LAS __attribute__((address_space(3)))
; __device__ __forceinline__ void convert_tiles(const Frame& F, int tlo, int thi, int wb, int nw) {
;     LAS float* tile = (LAS float*)F.lds;
;     int t = tlo + wb; if (t >= thi) return;
;     TileDesc d = tile_desc(F, t);
;     f32x4 v[8];
; #pragma unroll
;     for (int i = 0; i < 8; ++i) v[i] = __builtin_nontemporal_load((const f32x4*)(d.src + (size_t)(d.k0 + i * 8 + F.wave) * d.ldn + d.n0 + F.lane * 4));
;     for (;;) {
; #pragma unroll
;         for (int i = 0; i < 8; ++i) { LAS float* tp = tile + (i * 8 + F.wave) * 257 + F.lane * 4; tp[0] = v[i][0]; tp[1] = v[i][1]; tp[2] = v[i][2]; tp[3] = v[i][3]; }
;         __syncthreads();
;         const int tn = t + nw; const bool more = tn < thi; TileDesc dn = d;
;         if (more) { dn = tile_desc(F, tn);
; #pragma unroll
;             for (int i = 0; i < 8; ++i) v[i] = __builtin_nontemporal_load((const f32x4*)(dn.src + (size_t)(dn.k0 + i * 8 + F.wave) * dn.ldn + dn.n0 + F.lane * 4)); }
.LBB0_295:
	s_waitcnt vmcnt(0)
	s_barrier
	s_cmpk_lt_i32 s33, 236
	s_cbranch_scc1 .Lmy_cv3_end
	s_sub_i32 s12, s33, 236
	s_cmpk_ge_i32 s12, 16
	s_cbranch_scc1 .Lmy_cv3_end
	s_add_i32 s12, s12, 144
	s_load_dwordx2 s[4:5], s[98:99], 0x98
	s_add_u32 s6, s84, 0x4600000
	s_addc_u32 s7, s85, 0
	v_lshlrev_b32_e32 v32, 4, v160
	s_mul_i32 s16, s80, 0x404
	v_add_u32_e32 v33, s16, v32
	v_and_b32_e32 v36, 7, v144
	v_lshrrev_b32_e32 v35, 3, v144
	v_mul_u32_u24_e32 v34, 0x2020, v36
	v_lshl_add_u32 v34, v35, 2, v34
	v_mov_b32_e32 v37, 0x1000
	v_mul_u32_u24_e32 v35, v35, v37
	v_lshl_add_u32 v35, v36, 4, v35
	s_waitcnt lgkmcnt(0)
	s_lshr_b32 s16, s12, 3
	s_and_b32 s17, s12, 7
	s_lshl_b32 s18, s16, 19
	s_lshl_b32 s19, s80, 13
	s_add_i32 s18, s18, s19
	s_lshl_b32 s19, s17, 10
	s_add_i32 s18, s18, s19
	s_add_u32 s8, s4, s18
	s_addc_u32 s9, s5, 0
	s_mul_i32 s18, s17, 0x100000
	s_lshl_b32 s19, s16, 7
	s_add_i32 s18, s18, s19
	s_add_u32 s10, s6, s18
	s_addc_u32 s11, s7, 0
	global_load_dwordx4 v[0:3], v32, s[8:9] nt
	s_add_u32 s8, s8, 0x10000
	s_addc_u32 s9, s9, 0
	global_load_dwordx4 v[4:7], v32, s[8:9] nt
	s_add_u32 s8, s8, 0x10000
	s_addc_u32 s9, s9, 0
	global_load_dwordx4 v[8:11], v32, s[8:9] nt
	s_add_u32 s8, s8, 0x10000
	s_addc_u32 s9, s9, 0
	global_load_dwordx4 v[12:15], v32, s[8:9] nt
	s_add_u32 s8, s8, 0x10000
	s_addc_u32 s9, s9, 0
	global_load_dwordx4 v[16:19], v32, s[8:9] nt
	s_add_u32 s8, s8, 0x10000
	s_addc_u32 s9, s9, 0
	global_load_dwordx4 v[20:23], v32, s[8:9] nt
	s_add_u32 s8, s8, 0x10000
	s_addc_u32 s9, s9, 0
	global_load_dwordx4 v[24:27], v32, s[8:9] nt
	s_add_u32 s8, s8, 0x10000
	s_addc_u32 s9, s9, 0
	global_load_dwordx4 v[28:31], v32, s[8:9] nt
	s_waitcnt vmcnt(0)
.Lmy_cv3_loop:
	ds_write_b32 v33, v0 offset:0
	ds_write_b32 v33, v1 offset:4
	ds_write_b32 v33, v2 offset:8
	ds_write_b32 v33, v3 offset:12
	ds_write_b32 v33, v4 offset:8224
	ds_write_b32 v33, v5 offset:8228
	ds_write_b32 v33, v6 offset:8232
	ds_write_b32 v33, v7 offset:8236
	ds_write_b32 v33, v8 offset:16448
	ds_write_b32 v33, v9 offset:16452
	ds_write_b32 v33, v10 offset:16456
	ds_write_b32 v33, v11 offset:16460
	ds_write_b32 v33, v12 offset:24672
	ds_write_b32 v33, v13 offset:24676
	ds_write_b32 v33, v14 offset:24680
	ds_write_b32 v33, v15 offset:24684
	ds_write_b32 v33, v16 offset:32896
	ds_write_b32 v33, v17 offset:32900
	ds_write_b32 v33, v18 offset:32904
	ds_write_b32 v33, v19 offset:32908
	ds_write_b32 v33, v20 offset:41120
	ds_write_b32 v33, v21 offset:41124
	ds_write_b32 v33, v22 offset:41128
	ds_write_b32 v33, v23 offset:41132
	ds_write_b32 v33, v24 offset:49344
	ds_write_b32 v33, v25 offset:49348
	ds_write_b32 v33, v26 offset:49352
	ds_write_b32 v33, v27 offset:49356
	ds_write_b32 v33, v28 offset:57568
	ds_write_b32 v33, v29 offset:57572
	ds_write_b32 v33, v30 offset:57576
	ds_write_b32 v33, v31 offset:57580
	s_waitcnt lgkmcnt(0)
	s_barrier
	s_add_i32 s13, s12, 16
	s_cmpk_lt_i32 s13, 256
	s_cbranch_scc0 .Lmy_cv3_nopf
	s_lshr_b32 s16, s13, 3
	s_and_b32 s17, s13, 7
	s_lshl_b32 s18, s16, 19
	s_lshl_b32 s19, s80, 13
	s_add_i32 s18, s18, s19
	s_lshl_b32 s19, s17, 10
	s_add_i32 s18, s18, s19
	s_add_u32 s8, s4, s18
	s_addc_u32 s9, s5, 0
	s_mul_i32 s18, s17, 0x100000
	s_lshl_b32 s19, s16, 7
	s_add_i32 s18, s18, s19
	s_mov_b32 s20, s18
	global_load_dwordx4 v[0:3], v32, s[8:9] nt
	s_add_u32 s8, s8, 0x10000
	s_addc_u32 s9, s9, 0
	global_load_dwordx4 v[4:7], v32, s[8:9] nt
	s_add_u32 s8, s8, 0x10000
	s_addc_u32 s9, s9, 0
	global_load_dwordx4 v[8:11], v32, s[8:9] nt
	s_add_u32 s8, s8, 0x10000
	s_addc_u32 s9, s9, 0
	global_load_dwordx4 v[12:15], v32, s[8:9] nt
	s_add_u32 s8, s8, 0x10000
	s_addc_u32 s9, s9, 0
	global_load_dwordx4 v[16:19], v32, s[8:9] nt
	s_add_u32 s8, s8, 0x10000
	s_addc_u32 s9, s9, 0
	global_load_dwordx4 v[20:23], v32, s[8:9] nt
	s_add_u32 s8, s8, 0x10000
	s_addc_u32 s9, s9, 0
	global_load_dwordx4 v[24:27], v32, s[8:9] nt
	s_add_u32 s8, s8, 0x10000
	s_addc_u32 s9, s9, 0
	global_load_dwordx4 v[28:31], v32, s[8:9] nt
; __device__ __forceinline__ unsigned xb_add(unsigned* p, unsigned v) { return __hip_atomic_fetch_add(p, v, __ATOMIC_RELAXED, __HIP_MEMORY_SCOPE_AGENT); }
; __device__ __forceinline__ void xcd_barrier(const XcdBarrier& b) {
;     asm volatile("s_waitcnt vmcnt(0)" ::: "memory");
;     __syncthreads();
;     if (threadIdx.x == 0) {
;         unsigned* bar = b.bar;
;         __builtin_amdgcn_s_waitcnt(0);
;         unsigned nloc = b.st[0], nx = b.st[1];
;         if (nloc == 0u) { xcd_barrier_complete(bar, b.x, nloc, nx); b.st[0] = nloc; b.st[1] = nx; }
;         const unsigned old = xb_add(&bar[XB_XSUB(b.x)], 1u);
; __device__ __forceinline__ void convert_tiles(const Frame& F, int tlo, int thi, int wb, int nw) {
;     ...
;         for (int it = 0; it < 4; ++it) { const int item = it * 512 + F.tid, n = item >> 3, kg = item & 7;
;             float f[8];
; #pragma unroll
;             for (int j = 0; j < 8; ++j) f[j] = tile[(kg * 8 + j) * 257 + n];
;             const int nn = d.n0 + n; const int row = d.kind == 0 ? nn : (((nn >> 7) << 8) + (nn & 127) + (d.kind == 2 ? 128 : 0));
;             *(u32x4*)(d.dst + (size_t)row * d.K + d.k0 + kg * 8) = pack8(f); }
;         __syncthreads();
;         if (!more) break;
;         t = tn; d = dn;
;     }
.Lmy_cv3_nopf:
	ds_read_b32 v36, v34 offset:0
	ds_read_b32 v37, v34 offset:1028
	ds_read_b32 v38, v34 offset:2056
	ds_read_b32 v39, v34 offset:3084
	ds_read_b32 v40, v34 offset:4112
	ds_read_b32 v41, v34 offset:5140
	ds_read_b32 v42, v34 offset:6168
	ds_read_b32 v43, v34 offset:7196
	s_waitcnt lgkmcnt(0)
	v_cvt_pk_bf16_f32 v44, v36, v37
	v_cvt_pk_bf16_f32 v45, v38, v39
	v_cvt_pk_bf16_f32 v46, v40, v41
	v_cvt_pk_bf16_f32 v47, v42, v43
	global_store_dwordx4 v35, v[44:47], s[10:11]
	s_add_u32 s10, s10, 0x40000
	s_addc_u32 s11, s11, 0
	ds_read_b32 v36, v34 offset:256
	ds_read_b32 v37, v34 offset:1284
	ds_read_b32 v38, v34 offset:2312
	ds_read_b32 v39, v34 offset:3340
	ds_read_b32 v40, v34 offset:4368
	ds_read_b32 v41, v34 offset:5396
	ds_read_b32 v42, v34 offset:6424
	ds_read_b32 v43, v34 offset:7452
	s_waitcnt lgkmcnt(0)
	v_cvt_pk_bf16_f32 v44, v36, v37
	v_cvt_pk_bf16_f32 v45, v38, v39
	v_cvt_pk_bf16_f32 v46, v40, v41
	v_cvt_pk_bf16_f32 v47, v42, v43
	global_store_dwordx4 v35, v[44:47], s[10:11]
	s_add_u32 s10, s10, 0x40000
	s_addc_u32 s11, s11, 0
	ds_read_b32 v36, v34 offset:512
	ds_read_b32 v37, v34 offset:1540
	ds_read_b32 v38, v34 offset:2568
	ds_read_b32 v39, v34 offset:3596
	ds_read_b32 v40, v34 offset:4624
	ds_read_b32 v41, v34 offset:5652
	ds_read_b32 v42, v34 offset:6680
	ds_read_b32 v43, v34 offset:7708
	s_waitcnt lgkmcnt(0)
	v_cvt_pk_bf16_f32 v44, v36, v37
	v_cvt_pk_bf16_f32 v45, v38, v39
	v_cvt_pk_bf16_f32 v46, v40, v41
	v_cvt_pk_bf16_f32 v47, v42, v43
	global_store_dwordx4 v35, v[44:47], s[10:11]
	s_add_u32 s10, s10, 0x40000
	s_addc_u32 s11, s11, 0
	ds_read_b32 v36, v34 offset:768
	ds_read_b32 v37, v34 offset:1796
	ds_read_b32 v38, v34 offset:2824
	ds_read_b32 v39, v34 offset:3852
	ds_read_b32 v40, v34 offset:4880
	ds_read_b32 v41, v34 offset:5908
	ds_read_b32 v42, v34 offset:6936
	ds_read_b32 v43, v34 offset:7964
	s_waitcnt lgkmcnt(0)
	v_cvt_pk_bf16_f32 v44, v36, v37
	v_cvt_pk_bf16_f32 v45, v38, v39
	v_cvt_pk_bf16_f32 v46, v40, v41
	v_cvt_pk_bf16_f32 v47, v42, v43
	global_store_dwordx4 v35, v[44:47], s[10:11]
	s_barrier
	s_cmpk_lt_i32 s13, 256
	s_cbranch_scc0 .Lmy_cv3_end
	s_mov_b32 s12, s13
	s_add_u32 s10, s6, s20
	s_addc_u32 s11, s7, 0
	s_waitcnt vmcnt(4)
	s_branch .Lmy_cv3_loop
.Lmy_cv3_end:
.LBB0_296:
	s_cmp_gt_i32 s87, 4
	s_cselect_b64 s[2:3], -1, 0
	s_and_b64 s[4:5], s[14:15], s[2:3]
	s_andn2_b64 vcc, exec, s[4:5]
	s_cbranch_vccnz .LBB0_346
	s_waitcnt vmcnt(0)
	s_waitcnt vmcnt(0) lgkmcnt(0)
	s_barrier
	s_mov_b64 s[4:5], exec
	v_readlane_b32 s6, v245, 1
	v_readlane_b32 s7, v245, 2
	s_and_b64 s[6:7], s[4:5], s[6:7]
	s_mov_b64 exec, s[6:7]
	s_cbranch_execz .LBB0_345
	s_add_i32 s6, 0, 0x23ff0
	v_mov_b32_e32 v0, s6
	s_waitcnt vmcnt(0) expcnt(0) lgkmcnt(0)
	ds_read_b32 v2, v0
	s_add_i32 s6, 0, 0x23ff4
	v_mov_b32_e32 v0, s6
	ds_read_b32 v0, v0
	s_waitcnt lgkmcnt(1)
	v_cmp_ne_u32_e32 vcc, 0, v2
	s_cbranch_vccnz .LBB0_313
	s_load_dword s6, s[0:1], 0xe0
	s_mov_b32 s29, 1
	v_mov_b32_e32 v16, 0
	s_waitcnt lgkmcnt(0)
	s_mul_i32 s28, s89, s6
	s_add_u32 s6, s84, 0x1da00300
	s_addc_u32 s7, s85, 0
	s_add_u32 s8, s84, 0x1da00500
	s_addc_u32 s9, s85, 0
	s_add_u32 s10, s84, 0x1da00600
	s_addc_u32 s11, s85, 0
	s_add_u32 s12, s84, 0x1da00700
	s_addc_u32 s13, s85, 0
	s_add_u32 s14, s84, 0x1da00800
	s_addc_u32 s15, s85, 0
	s_add_u32 s16, s84, 0x1da00900
	s_addc_u32 s17, s85, 0
	s_add_u32 s18, s84, 0x1da00a00
	s_addc_u32 s19, s85, 0
	s_add_u32 s20, s84, 0x1da00b00
	s_addc_u32 s21, s85, 0
	s_add_u32 s22, s84, 0x1da00c00
	s_addc_u32 s23, s85, 0
	s_add_u32 s24, s84, 0x1da00d00
	s_addc_u32 s25, s85, 0
	s_add_u32 s26, s84, 0x1da00e00
	s_addc_u32 s27, s85, 0
	s_add_u32 s30, s84, 0x1da00f00
	s_addc_u32 s31, s85, 0
	s_add_u32 s34, s84, 0x1da01000
	s_addc_u32 s35, s85, 0
	s_add_u32 s42, s84, 0x1da01100
	s_addc_u32 s43, s85, 0
	s_add_u32 s44, s84, 0x1da01200
	s_addc_u32 s45, s85, 0
	s_add_u32 s46, s84, 0x1da01300
	s_addc_u32 s47, s85, 0
	s_add_u32 s48, s84, 0x1da01400
	s_mul_i32 s28, s28, s88
	s_addc_u32 s49, s85, 0
	s_branch .LBB0_301

; #define LAS __attribute__((address_space(3)))
; __device__ __forceinline__ void convert_tiles(const Frame& F, int tlo, int thi, int wb, int nw) {
;     LAS float* tile = (LAS float*)F.lds;
;     int t = tlo + wb; if (t >= thi) return;
;     TileDesc d = tile_desc(F, t);
;     f32x4 v[8];
; #pragma unroll
;     for (int i = 0; i < 8; ++i) v[i] = __builtin_nontemporal_load((const f32x4*)(d.src + (size_t)(d.k0 + i * 8 + F.wave) * d.ldn + d.n0 + F.lane * 4));
;     for (;;) {
; #pragma unroll
;         for (int i = 0; i < 8; ++i) { LAS float* tp = tile + (i * 8 + F.wave) * 257 + F.lane * 4; tp[0] = v[i][0]; tp[1] = v[i][1]; tp[2] = v[i][2]; tp[3] = v[i][3]; }
;         __syncthreads();
;         const int tn = t + nw; const bool more = tn < thi; TileDesc dn = d;
;         if (more) { dn = tile_desc(F, tn);
; #pragma unroll
;             for (int i = 0; i < 8; ++i) v[i] = __builtin_nontemporal_load((const f32x4*)(dn.src + (size_t)(dn.k0 + i * 8 + F.wave) * dn.ldn + dn.n0 + F.lane * 4)); }
.LBB0_1034:
	s_waitcnt vmcnt(0)
	s_barrier
	s_cmpk_lt_i32 s33, 216
	s_cbranch_scc1 .Lmy_cv9_end
	s_sub_i32 s12, s33, 216
	s_cmpk_ge_i32 s12, 40
	s_cbranch_scc1 .Lmy_cv9_end
	s_add_i32 s12, s12, 304
	s_load_dwordx2 s[4:5], s[98:99], 0xb0
	s_add_u32 s6, s84, 0x7a00000
	s_addc_u32 s7, s85, 0
	v_lshlrev_b32_e32 v32, 4, v160
	s_mul_i32 s16, s80, 0x404
	v_add_u32_e32 v33, s16, v32
	v_and_b32_e32 v36, 7, v144
	v_lshrrev_b32_e32 v35, 3, v144
	v_mul_u32_u24_e32 v34, 0x2020, v36
	v_lshl_add_u32 v34, v35, 2, v34
	v_mov_b32_e32 v37, 0x2c00
	v_mul_u32_u24_e32 v35, v35, v37
	v_lshl_add_u32 v35, v36, 4, v35
	s_waitcnt lgkmcnt(0)
	s_lshr_b32 s16, s12, 3
	s_and_b32 s17, s12, 7
	s_lshl_b32 s18, s16, 19
	s_lshl_b32 s19, s80, 13
	s_add_i32 s18, s18, s19
	s_lshl_b32 s19, s17, 10
	s_add_i32 s18, s18, s19
	s_add_u32 s8, s4, s18
	s_addc_u32 s9, s5, 0
	s_mul_i32 s18, s17, 0x2c0000
	s_lshl_b32 s19, s16, 7
	s_add_i32 s18, s18, s19
	s_add_u32 s10, s6, s18
	s_addc_u32 s11, s7, 0
	global_load_dwordx4 v[0:3], v32, s[8:9] nt
	s_add_u32 s8, s8, 0x10000
	s_addc_u32 s9, s9, 0
	global_load_dwordx4 v[4:7], v32, s[8:9] nt
	s_add_u32 s8, s8, 0x10000
	s_addc_u32 s9, s9, 0
	global_load_dwordx4 v[8:11], v32, s[8:9] nt
	s_add_u32 s8, s8, 0x10000
	s_addc_u32 s9, s9, 0
	global_load_dwordx4 v[12:15], v32, s[8:9] nt
	s_add_u32 s8, s8, 0x10000
	s_addc_u32 s9, s9, 0
	global_load_dwordx4 v[16:19], v32, s[8:9] nt
	s_add_u32 s8, s8, 0x10000
	s_addc_u32 s9, s9, 0
	global_load_dwordx4 v[20:23], v32, s[8:9] nt
	s_add_u32 s8, s8, 0x10000
	s_addc_u32 s9, s9, 0
	global_load_dwordx4 v[24:27], v32, s[8:9] nt
	s_add_u32 s8, s8, 0x10000
	s_addc_u32 s9, s9, 0
	global_load_dwordx4 v[28:31], v32, s[8:9] nt
	s_waitcnt vmcnt(0)
.Lmy_cv9_loop:
	ds_write_b32 v33, v0 offset:0
	ds_write_b32 v33, v1 offset:4
	ds_write_b32 v33, v2 offset:8
	ds_write_b32 v33, v3 offset:12
	ds_write_b32 v33, v4 offset:8224
	ds_write_b32 v33, v5 offset:8228
	ds_write_b32 v33, v6 offset:8232
	ds_write_b32 v33, v7 offset:8236
	ds_write_b32 v33, v8 offset:16448
	ds_write_b32 v33, v9 offset:16452
	ds_write_b32 v33, v10 offset:16456
	ds_write_b32 v33, v11 offset:16460
	ds_write_b32 v33, v12 offset:24672
	ds_write_b32 v33, v13 offset:24676
	ds_write_b32 v33, v14 offset:24680
	ds_write_b32 v33, v15 offset:24684
	ds_write_b32 v33, v16 offset:32896
	ds_write_b32 v33, v17 offset:32900
	ds_write_b32 v33, v18 offset:32904
	ds_write_b32 v33, v19 offset:32908
	ds_write_b32 v33, v20 offset:41120
	ds_write_b32 v33, v21 offset:41124
	ds_write_b32 v33, v22 offset:41128
	ds_write_b32 v33, v23 offset:41132
	ds_write_b32 v33, v24 offset:49344
	ds_write_b32 v33, v25 offset:49348
	ds_write_b32 v33, v26 offset:49352
	ds_write_b32 v33, v27 offset:49356
	ds_write_b32 v33, v28 offset:57568
	ds_write_b32 v33, v29 offset:57572
	ds_write_b32 v33, v30 offset:57576
	ds_write_b32 v33, v31 offset:57580
	s_waitcnt lgkmcnt(0)
	s_barrier
	s_add_i32 s13, s12, 40
	s_cmpk_lt_i32 s13, 704
	s_cbranch_scc0 .Lmy_cv9_nopf
	s_lshr_b32 s16, s13, 3
	s_and_b32 s17, s13, 7
	s_lshl_b32 s18, s16, 19
	s_lshl_b32 s19, s80, 13
	s_add_i32 s18, s18, s19
	s_lshl_b32 s19, s17, 10
	s_add_i32 s18, s18, s19
	s_add_u32 s8, s4, s18
	s_addc_u32 s9, s5, 0
	s_mul_i32 s18, s17, 0x2c0000
	s_lshl_b32 s19, s16, 7
	s_add_i32 s18, s18, s19
	s_mov_b32 s20, s18
	global_load_dwordx4 v[0:3], v32, s[8:9] nt
	s_add_u32 s8, s8, 0x10000
	s_addc_u32 s9, s9, 0
	global_load_dwordx4 v[4:7], v32, s[8:9] nt
	s_add_u32 s8, s8, 0x10000
	s_addc_u32 s9, s9, 0
	global_load_dwordx4 v[8:11], v32, s[8:9] nt
	s_add_u32 s8, s8, 0x10000
	s_addc_u32 s9, s9, 0
	global_load_dwordx4 v[12:15], v32, s[8:9] nt
	s_add_u32 s8, s8, 0x10000
	s_addc_u32 s9, s9, 0
	global_load_dwordx4 v[16:19], v32, s[8:9] nt
	s_add_u32 s8, s8, 0x10000
	s_addc_u32 s9, s9, 0
	global_load_dwordx4 v[20:23], v32, s[8:9] nt
	s_add_u32 s8, s8, 0x10000
	s_addc_u32 s9, s9, 0
	global_load_dwordx4 v[24:27], v32, s[8:9] nt
	s_add_u32 s8, s8, 0x10000
	s_addc_u32 s9, s9, 0
	global_load_dwordx4 v[28:31], v32, s[8:9] nt
; __device__ __forceinline__ unsigned xb_add(unsigned* p, unsigned v) { return __hip_atomic_fetch_add(p, v, __ATOMIC_RELAXED, __HIP_MEMORY_SCOPE_AGENT); }
; __device__ __forceinline__ void xcd_barrier(const XcdBarrier& b) {
;     asm volatile("s_waitcnt vmcnt(0)" ::: "memory");
;     __syncthreads();
;     if (threadIdx.x == 0) {
;         unsigned* bar = b.bar;
;         __builtin_amdgcn_s_waitcnt(0);
;         unsigned nloc = b.st[0], nx = b.st[1];
;         if (nloc == 0u) { xcd_barrier_complete(bar, b.x, nloc, nx); b.st[0] = nloc; b.st[1] = nx; }
;         const unsigned old = xb_add(&bar[XB_XSUB(b.x)], 1u);
; __device__ __forceinline__ void convert_tiles(const Frame& F, int tlo, int thi, int wb, int nw) {
;     ...
;         for (int it = 0; it < 4; ++it) { const int item = it * 512 + F.tid, n = item >> 3, kg = item & 7;
;             float f[8];
; #pragma unroll
;             for (int j = 0; j < 8; ++j) f[j] = tile[(kg * 8 + j) * 257 + n];
;             const int nn = d.n0 + n; const int row = d.kind == 0 ? nn : (((nn >> 7) << 8) + (nn & 127) + (d.kind == 2 ? 128 : 0));
;             *(u32x4*)(d.dst + (size_t)row * d.K + d.k0 + kg * 8) = pack8(f); }
;         __syncthreads();
;         if (!more) break;
;         t = tn; d = dn;
;     }
.Lmy_cv9_nopf:
	ds_read_b32 v36, v34 offset:0
	ds_read_b32 v37, v34 offset:1028
	ds_read_b32 v38, v34 offset:2056
	ds_read_b32 v39, v34 offset:3084
	ds_read_b32 v40, v34 offset:4112
	ds_read_b32 v41, v34 offset:5140
	ds_read_b32 v42, v34 offset:6168
	ds_read_b32 v43, v34 offset:7196
	s_waitcnt lgkmcnt(0)
	v_cvt_pk_bf16_f32 v44, v36, v37
	v_cvt_pk_bf16_f32 v45, v38, v39
	v_cvt_pk_bf16_f32 v46, v40, v41
	v_cvt_pk_bf16_f32 v47, v42, v43
	global_store_dwordx4 v35, v[44:47], s[10:11]
	s_add_u32 s10, s10, 0xb0000
	s_addc_u32 s11, s11, 0
	ds_read_b32 v36, v34 offset:256
	ds_read_b32 v37, v34 offset:1284
	ds_read_b32 v38, v34 offset:2312
	ds_read_b32 v39, v34 offset:3340
	ds_read_b32 v40, v34 offset:4368
	ds_read_b32 v41, v34 offset:5396
	ds_read_b32 v42, v34 offset:6424
	ds_read_b32 v43, v34 offset:7452
	s_waitcnt lgkmcnt(0)
	v_cvt_pk_bf16_f32 v44, v36, v37
	v_cvt_pk_bf16_f32 v45, v38, v39
	v_cvt_pk_bf16_f32 v46, v40, v41
	v_cvt_pk_bf16_f32 v47, v42, v43
	global_store_dwordx4 v35, v[44:47], s[10:11]
	s_add_u32 s10, s10, 0xb0000
	s_addc_u32 s11, s11, 0
	ds_read_b32 v36, v34 offset:512
	ds_read_b32 v37, v34 offset:1540
	ds_read_b32 v38, v34 offset:2568
	ds_read_b32 v39, v34 offset:3596
	ds_read_b32 v40, v34 offset:4624
	ds_read_b32 v41, v34 offset:5652
	ds_read_b32 v42, v34 offset:6680
	ds_read_b32 v43, v34 offset:7708
	s_waitcnt lgkmcnt(0)
	v_cvt_pk_bf16_f32 v44, v36, v37
	v_cvt_pk_bf16_f32 v45, v38, v39
	v_cvt_pk_bf16_f32 v46, v40, v41
	v_cvt_pk_bf16_f32 v47, v42, v43
	global_store_dwordx4 v35, v[44:47], s[10:11]
	s_add_u32 s10, s10, 0xb0000
	s_addc_u32 s11, s11, 0
	ds_read_b32 v36, v34 offset:768
	ds_read_b32 v37, v34 offset:1796
	ds_read_b32 v38, v34 offset:2824
	ds_read_b32 v39, v34 offset:3852
	ds_read_b32 v40, v34 offset:4880
	ds_read_b32 v41, v34 offset:5908
	ds_read_b32 v42, v34 offset:6936
	ds_read_b32 v43, v34 offset:7964
	s_waitcnt lgkmcnt(0)
	v_cvt_pk_bf16_f32 v44, v36, v37
	v_cvt_pk_bf16_f32 v45, v38, v39
	v_cvt_pk_bf16_f32 v46, v40, v41
	v_cvt_pk_bf16_f32 v47, v42, v43
	global_store_dwordx4 v35, v[44:47], s[10:11]
	s_barrier
	s_cmpk_lt_i32 s13, 704
	s_cbranch_scc0 .Lmy_cv9_end
	s_mov_b32 s12, s13
	s_add_u32 s10, s6, s20
	s_addc_u32 s11, s7, 0
	s_waitcnt vmcnt(4)
	s_branch .Lmy_cv9_loop
.Lmy_cv9_end:
.LBB0_1035:
	s_cmp_gt_i32 s87, 10
	s_cselect_b64 s[0:1], -1, 0
	s_and_b64 s[2:3], s[2:3], s[0:1]
	s_andn2_b64 vcc, exec, s[2:3]
	s_cbranch_vccnz .LBB0_1085
	s_waitcnt vmcnt(0)
	s_waitcnt vmcnt(0)
	s_barrier
	s_mov_b64 s[2:3], exec
	v_readlane_b32 s4, v245, 1
	v_readlane_b32 s5, v245, 2
	s_and_b64 s[4:5], s[2:3], s[4:5]
	s_mov_b64 exec, s[4:5]
	s_cbranch_execz .LBB0_1084
	s_add_i32 s4, 0, 0x23ff0
	v_mov_b32_e32 v0, s4
	s_waitcnt vmcnt(0) expcnt(0) lgkmcnt(0)
	ds_read_b32 v2, v0
	s_add_i32 s4, 0, 0x23ff4
	v_mov_b32_e32 v0, s4
	ds_read_b32 v0, v0
	s_waitcnt lgkmcnt(1)
	v_cmp_ne_u32_e32 vcc, 0, v2
	s_cbranch_vccnz .LBB0_1052
	v_readlane_b32 s4, v245, 0
	s_mul_i32 s28, s89, s4
	s_add_u32 s4, s84, 0x1da00300
	s_addc_u32 s5, s85, 0
	s_add_u32 s6, s84, 0x1da00500
	s_addc_u32 s7, s85, 0
	s_add_u32 s8, s84, 0x1da00600
	s_addc_u32 s9, s85, 0
	s_add_u32 s10, s84, 0x1da00700
	s_addc_u32 s11, s85, 0
	s_add_u32 s12, s84, 0x1da00800
	s_addc_u32 s13, s85, 0
	s_add_u32 s14, s84, 0x1da00900
	s_addc_u32 s15, s85, 0
	s_add_u32 s16, s84, 0x1da00a00
	s_addc_u32 s17, s85, 0
	s_add_u32 s18, s84, 0x1da00b00
	s_addc_u32 s19, s85, 0
	s_add_u32 s20, s84, 0x1da00c00
	s_addc_u32 s21, s85, 0
	s_add_u32 s22, s84, 0x1da00d00
	s_addc_u32 s23, s85, 0
	s_add_u32 s24, s84, 0x1da00e00
	s_addc_u32 s25, s85, 0
	s_add_u32 s26, s84, 0x1da00f00
	s_addc_u32 s27, s85, 0
	s_add_u32 s30, s84, 0x1da01000
	s_addc_u32 s31, s85, 0
	s_add_u32 s34, s84, 0x1da01100
	s_addc_u32 s35, s85, 0
	s_add_u32 s36, s84, 0x1da01200
	s_addc_u32 s37, s85, 0
	s_add_u32 s38, s84, 0x1da01300
	s_addc_u32 s39, s85, 0
	s_add_u32 s40, s84, 0x1da01400
	s_mul_i32 s28, s28, s88
	s_addc_u32 s41, s85, 0
	s_mov_b32 s29, 1
	v_mov_b32_e32 v16, 0
	s_branch .LBB0_1040

; __global__ void __launch_bounds__(512, 2) fwd_mega(Params prm) {
	.amdhsa_kernel _Z8fwd_mega6Params
		.amdhsa_group_segment_fixed_size 0
		.amdhsa_private_segment_fixed_size 0
		.amdhsa_kernarg_size 472
		.amdhsa_user_sgpr_count 2
		.amdhsa_user_sgpr_dispatch_ptr 0
		.amdhsa_user_sgpr_queue_ptr 0
		.amdhsa_user_sgpr_kernarg_segment_ptr 1
		.amdhsa_user_sgpr_dispatch_id 0
		.amdhsa_user_sgpr_kernarg_preload_length 0
		.amdhsa_user_sgpr_kernarg_preload_offset 0
		.amdhsa_user_sgpr_private_segment_size 0
		.amdhsa_uses_dynamic_stack 0
		.amdhsa_enable_private_segment 0
		.amdhsa_system_sgpr_workgroup_id_x 1
		.amdhsa_system_sgpr_workgroup_id_y 0
		.amdhsa_system_sgpr_workgroup_id_z 0
		.amdhsa_system_sgpr_workgroup_info 0
		.amdhsa_system_vgpr_workitem_id 2
		.amdhsa_next_free_vgpr 246
		.amdhsa_next_free_sgpr 100
		.amdhsa_accum_offset 248
		.amdhsa_reserve_vcc 1
		.amdhsa_float_round_mode_32 0
		.amdhsa_float_round_mode_16_64 0
		.amdhsa_float_denorm_mode_32 3
		.amdhsa_float_denorm_mode_16_64 3
		.amdhsa_dx10_clamp 1
		.amdhsa_ieee_mode 1
		.amdhsa_fp16_overflow 0
		.amdhsa_tg_split 0
		.amdhsa_exception_fp_ieee_invalid_op 0
		.amdhsa_exception_fp_denorm_src 0
		.amdhsa_exception_fp_ieee_div_zero 0
		.amdhsa_exception_fp_ieee_overflow 0
		.amdhsa_exception_fp_ieee_underflow 0
		.amdhsa_exception_fp_ieee_inexact 0
		.amdhsa_exception_int_div_zero 0
	.end_amdhsa_kernel

; __global__ void __launch_bounds__(512, 2) fwd_mega(Params prm) {
amdhsa.kernels:
  - .agpr_count:     0
    .args:
      - .offset:         0
        .size:           216
        .value_kind:     by_value
      - .offset:         216
        .size:           4
        .value_kind:     hidden_block_count_x
      - .offset:         220
        .size:           4
        .value_kind:     hidden_block_count_y
      - .offset:         224
        .size:           4
        .value_kind:     hidden_block_count_z
      - .offset:         228
        .size:           2
        .value_kind:     hidden_group_size_x
      - .offset:         230
        .size:           2
        .value_kind:     hidden_group_size_y
      - .offset:         232
        .size:           2
        .value_kind:     hidden_group_size_z
      - .offset:         234
        .size:           2
        .value_kind:     hidden_remainder_x
      - .offset:         236
        .size:           2
        .value_kind:     hidden_remainder_y
      - .offset:         238
        .size:           2
        .value_kind:     hidden_remainder_z
      - .offset:         256
        .size:           8
        .value_kind:     hidden_global_offset_x
      - .offset:         264
        .size:           8
        .value_kind:     hidden_global_offset_y
      - .offset:         272
        .size:           8
        .value_kind:     hidden_global_offset_z
      - .offset:         280
        .size:           2
        .value_kind:     hidden_grid_dims
      - .offset:         304
        .size:           8
        .value_kind:     hidden_multigrid_sync_arg
      - .offset:         336
        .size:           4
        .value_kind:     hidden_dynamic_lds_size
    .group_segment_fixed_size: 0
    .kernarg_segment_align: 8
    .kernarg_segment_size: 472
    .language:       OpenCL C
    .language_version:
      - 2
      - 0
    .max_flat_workgroup_size: 512
    .name:           _Z8fwd_mega6Params
    .private_segment_fixed_size: 0
    .sgpr_count:     106
    .sgpr_spill_count: 65
    .symbol:         _Z8fwd_mega6Params.kd
    .uniform_work_group_size: 1
    .uses_dynamic_stack: false
    .vgpr_count:     246
    .vgpr_spill_count: 0
    .wavefront_size: 64
